# v33 plus agent-scope streaming policy (sc1 nt) on the sample attention K/V cache loads
# speedup vs baseline: 1.0044x; 1.0044x over previous
.LBB11_2193:
	s_lshl_b32 s1, s0, 4
	s_or_b32 s60, s1, s76
	s_lshl_b64 s[48:49], s[60:61], 12
	s_waitcnt lgkmcnt(0)
	v_lshl_add_u64 v[2:3], v[62:63], 0, s[48:49]
	s_or_b32 s48, s60, 1
	s_mov_b32 s49, s61
	s_lshl_b64 s[48:49], s[48:49], 12
	v_lshl_add_u64 v[4:5], v[62:63], 0, s[48:49]
	global_load_dwordx4 v[68:71], v[2:3], off sc1 nt
	global_load_dwordx4 v[58:61], v[4:5], off sc1 nt
	s_or_b32 s48, s60, 2
	s_mov_b32 s49, s61
	s_lshl_b64 s[48:49], s[48:49], 12
	v_lshl_add_u64 v[2:3], v[62:63], 0, s[48:49]
	s_or_b32 s48, s60, 3
	s_mov_b32 s49, s61
	s_lshl_b64 s[48:49], s[48:49], 12
	v_lshl_add_u64 v[4:5], v[62:63], 0, s[48:49]
	s_or_b32 s48, s60, 4
	s_mov_b32 s49, s61
	s_lshl_b64 s[48:49], s[48:49], 12
	global_load_dwordx4 v[54:57], v[2:3], off sc1 nt
	global_load_dwordx4 v[50:53], v[4:5], off sc1 nt
	v_lshl_add_u64 v[2:3], v[62:63], 0, s[48:49]
	s_or_b32 s48, s60, 5
	s_mov_b32 s49, s61
	s_lshl_b64 s[48:49], s[48:49], 12
	v_lshl_add_u64 v[4:5], v[62:63], 0, s[48:49]
	s_or_b32 s48, s60, 6
	s_mov_b32 s49, s61
	s_lshl_b64 s[48:49], s[48:49], 12
	global_load_dwordx4 v[46:49], v[2:3], off sc1 nt
	global_load_dwordx4 v[42:45], v[4:5], off sc1 nt
	v_lshl_add_u64 v[2:3], v[62:63], 0, s[48:49]
	s_or_b32 s48, s60, 7
	s_mov_b32 s49, s61
	s_lshl_b64 s[48:49], s[48:49], 12
	v_lshl_add_u64 v[4:5], v[62:63], 0, s[48:49]
	s_or_b32 s48, s60, 8
	s_mov_b32 s49, s61
	s_lshl_b64 s[48:49], s[48:49], 12
	global_load_dwordx4 v[38:41], v[2:3], off sc1 nt
	global_load_dwordx4 v[34:37], v[4:5], off sc1 nt
	v_lshl_add_u64 v[2:3], v[62:63], 0, s[48:49]
	s_or_b32 s48, s60, 9
	s_mov_b32 s49, s61
	s_lshl_b64 s[48:49], s[48:49], 12
	v_lshl_add_u64 v[4:5], v[62:63], 0, s[48:49]
	s_or_b32 s48, s60, 10
	s_mov_b32 s49, s61
	s_lshl_b64 s[48:49], s[48:49], 12
	global_load_dwordx4 v[30:33], v[2:3], off sc1 nt
	global_load_dwordx4 v[26:29], v[4:5], off sc1 nt
	v_lshl_add_u64 v[2:3], v[62:63], 0, s[48:49]
	s_or_b32 s48, s60, 11
	s_mov_b32 s49, s61
	s_lshl_b64 s[48:49], s[48:49], 12
	v_lshl_add_u64 v[4:5], v[62:63], 0, s[48:49]
	s_or_b32 s48, s60, 12
	s_mov_b32 s49, s61
	s_lshl_b64 s[48:49], s[48:49], 12
	global_load_dwordx4 v[22:25], v[2:3], off sc1 nt
	global_load_dwordx4 v[18:21], v[4:5], off sc1 nt
	v_lshl_add_u64 v[2:3], v[62:63], 0, s[48:49]
	s_or_b32 s48, s60, 13
	s_mov_b32 s49, s61
	s_lshl_b64 s[48:49], s[48:49], 12
	v_lshl_add_u64 v[4:5], v[62:63], 0, s[48:49]
	s_or_b32 s48, s60, 14
	s_mov_b32 s49, s61
	s_lshl_b64 s[48:49], s[48:49], 12
	s_or_b32 s60, s60, 15
	global_load_dwordx4 v[14:17], v[2:3], off sc1 nt
	global_load_dwordx4 v[10:13], v[4:5], off sc1 nt
	v_lshl_add_u64 v[2:3], v[62:63], 0, s[48:49]
	s_lshl_b64 s[48:49], s[60:61], 12
	v_lshl_add_u64 v[4:5], v[62:63], 0, s[48:49]
	global_load_dwordx4 v[6:9], v[2:3], off sc1 nt
	s_nop 0
	global_load_dwordx4 v[2:5], v[4:5], off sc1 nt
	s_lshl_b32 s60, s0, 6
	s_waitcnt vmcnt(15)
	v_lshlrev_b32_e32 v64, 16, v176
	v_and_b32_e32 v65, 0xffff0000, v176
	v_lshlrev_b32_e32 v66, 16, v177
	v_and_b32_e32 v67, 0xffff0000, v177
	v_mul_f32_e32 v69, v69, v65
	v_mul_f32_e32 v71, v71, v67
	v_fmac_f32_e32 v69, v68, v64
	v_fmac_f32_e32 v71, v70, v66
	v_add_f32_e32 v68, v69, v71
	s_waitcnt vmcnt(14)
	v_mul_f32_e32 v59, v59, v65
	v_fmac_f32_e32 v59, v58, v64
	v_mul_f32_e32 v58, v61, v67
	v_fmac_f32_e32 v58, v60, v66
	v_add_f32_e32 v58, v59, v58
	s_waitcnt vmcnt(13)
	v_mul_f32_e32 v55, v55, v65
	v_fmac_f32_e32 v55, v54, v64
	v_mul_f32_e32 v54, v57, v67
	v_fmac_f32_e32 v54, v56, v66
	v_add_f32_e32 v54, v55, v54
	s_waitcnt vmcnt(12)
	v_mul_f32_e32 v51, v51, v65
	v_fmac_f32_e32 v51, v50, v64
	v_mul_f32_e32 v50, v53, v67
	v_fmac_f32_e32 v50, v52, v66
	v_add_f32_e32 v50, v51, v50
	s_waitcnt vmcnt(11)
	v_mul_f32_e32 v47, v47, v65
	v_fmac_f32_e32 v47, v46, v64
	v_mul_f32_e32 v46, v49, v67
	v_fmac_f32_e32 v46, v48, v66
	v_add_f32_e32 v46, v47, v46
	s_waitcnt vmcnt(10)
	v_mul_f32_e32 v43, v43, v65
	v_fmac_f32_e32 v43, v42, v64
	v_mul_f32_e32 v42, v45, v67
	v_fmac_f32_e32 v42, v44, v66
	v_add_f32_e32 v42, v43, v42
	s_waitcnt vmcnt(9)
	v_mul_f32_e32 v39, v39, v65
	v_fmac_f32_e32 v39, v38, v64
	v_mul_f32_e32 v38, v41, v67
	v_fmac_f32_e32 v38, v40, v66
	v_add_f32_e32 v38, v39, v38
	s_waitcnt vmcnt(8)
	v_mul_f32_e32 v35, v35, v65
	v_fmac_f32_e32 v35, v34, v64
	v_mul_f32_e32 v34, v37, v67
	v_fmac_f32_e32 v34, v36, v66
	v_add_f32_e32 v34, v35, v34
	s_waitcnt vmcnt(7)
	v_mul_f32_e32 v31, v31, v65
	v_fmac_f32_e32 v31, v30, v64
	v_mul_f32_e32 v30, v33, v67
	v_fmac_f32_e32 v30, v32, v66
	v_add_f32_e32 v30, v31, v30
	s_waitcnt vmcnt(6)
	v_mul_f32_e32 v27, v27, v65
	v_fmac_f32_e32 v27, v26, v64
	v_mul_f32_e32 v26, v29, v67
	v_fmac_f32_e32 v26, v28, v66
	v_add_f32_e32 v26, v27, v26
	s_waitcnt vmcnt(5)
	v_mul_f32_e32 v23, v23, v65
	v_fmac_f32_e32 v23, v22, v64
	v_mul_f32_e32 v22, v25, v67
	v_fmac_f32_e32 v22, v24, v66
	v_add_f32_e32 v22, v23, v22
	s_waitcnt vmcnt(4)
	v_mul_f32_e32 v19, v19, v65
	v_fmac_f32_e32 v19, v18, v64
	v_mul_f32_e32 v18, v21, v67
	v_fmac_f32_e32 v18, v20, v66
	v_add_f32_e32 v18, v19, v18
	s_waitcnt vmcnt(3)
	v_mul_f32_e32 v15, v15, v65
	v_fmac_f32_e32 v15, v14, v64
	v_mul_f32_e32 v14, v17, v67
	v_fmac_f32_e32 v14, v16, v66
	v_add_f32_e32 v14, v15, v14
	s_waitcnt vmcnt(2)
	v_mul_f32_e32 v11, v11, v65
	v_fmac_f32_e32 v11, v10, v64
	v_mul_f32_e32 v10, v13, v67
	v_fmac_f32_e32 v10, v12, v66
	v_add_f32_e32 v10, v11, v10
	s_waitcnt vmcnt(1)
	v_mul_f32_e32 v7, v7, v65
	v_fmac_f32_e32 v7, v6, v64
	v_mul_f32_e32 v6, v9, v67
	v_fmac_f32_e32 v6, v8, v66
	v_add_f32_e32 v6, v7, v6
	s_waitcnt vmcnt(0)
	v_mul_f32_e32 v3, v3, v65
	v_fmac_f32_e32 v3, v2, v64
	v_mul_f32_e32 v2, v5, v67
	v_fmac_f32_e32 v2, v4, v66
	v_add_f32_e32 v2, v3, v2
	ds_bpermute_b32 v69, v200, v68
	ds_bpermute_b32 v59, v200, v58
	ds_bpermute_b32 v55, v200, v54
	ds_bpermute_b32 v51, v200, v50
	ds_bpermute_b32 v47, v200, v46
	ds_bpermute_b32 v43, v200, v42
	ds_bpermute_b32 v39, v200, v38
	ds_bpermute_b32 v35, v200, v34
	s_waitcnt lgkmcnt(7)
	v_add_f32_e32 v68, v68, v69
	s_waitcnt lgkmcnt(6)
	v_add_f32_e32 v58, v58, v59
	s_waitcnt lgkmcnt(5)
	v_add_f32_e32 v54, v54, v55
	s_waitcnt lgkmcnt(4)
	v_add_f32_e32 v50, v50, v51
	s_waitcnt lgkmcnt(3)
	v_add_f32_e32 v46, v46, v47
	s_waitcnt lgkmcnt(2)
	v_add_f32_e32 v42, v42, v43
	s_waitcnt lgkmcnt(1)
	v_add_f32_e32 v38, v38, v39
	s_waitcnt lgkmcnt(0)
	v_add_f32_e32 v34, v34, v35
	ds_bpermute_b32 v69, v201, v68
	ds_bpermute_b32 v59, v201, v58
	ds_bpermute_b32 v55, v201, v54
	ds_bpermute_b32 v51, v201, v50
	ds_bpermute_b32 v47, v201, v46
	ds_bpermute_b32 v43, v201, v42
	ds_bpermute_b32 v39, v201, v38
	ds_bpermute_b32 v35, v201, v34
	s_waitcnt lgkmcnt(7)
	v_add_f32_e32 v68, v68, v69
	s_waitcnt lgkmcnt(6)
	v_add_f32_e32 v58, v58, v59
	s_waitcnt lgkmcnt(5)
	v_add_f32_e32 v54, v54, v55
	s_waitcnt lgkmcnt(4)
	v_add_f32_e32 v50, v50, v51
	s_waitcnt lgkmcnt(3)
	v_add_f32_e32 v46, v46, v47
	s_waitcnt lgkmcnt(2)
	v_add_f32_e32 v42, v42, v43
	s_waitcnt lgkmcnt(1)
	v_add_f32_e32 v38, v38, v39
	s_waitcnt lgkmcnt(0)
	v_add_f32_e32 v34, v34, v35
	ds_bpermute_b32 v69, v202, v68
	ds_bpermute_b32 v59, v202, v58
	ds_bpermute_b32 v55, v202, v54
	ds_bpermute_b32 v51, v202, v50
	ds_bpermute_b32 v47, v202, v46
	ds_bpermute_b32 v43, v202, v42
	ds_bpermute_b32 v39, v202, v38
	ds_bpermute_b32 v35, v202, v34
	s_waitcnt lgkmcnt(7)
	v_add_f32_e32 v68, v68, v69
	s_waitcnt lgkmcnt(6)
	v_add_f32_e32 v58, v58, v59
	s_waitcnt lgkmcnt(5)
	v_add_f32_e32 v54, v54, v55
	s_waitcnt lgkmcnt(4)
	v_add_f32_e32 v50, v50, v51
	s_waitcnt lgkmcnt(3)
	v_add_f32_e32 v46, v46, v47
	s_waitcnt lgkmcnt(2)
	v_add_f32_e32 v42, v42, v43
	s_waitcnt lgkmcnt(1)
	v_add_f32_e32 v38, v38, v39
	s_waitcnt lgkmcnt(0)
	v_add_f32_e32 v34, v34, v35
	ds_bpermute_b32 v69, v203, v68
	ds_bpermute_b32 v59, v203, v58
	ds_bpermute_b32 v55, v203, v54
	ds_bpermute_b32 v51, v203, v50
	ds_bpermute_b32 v47, v203, v46
	ds_bpermute_b32 v43, v203, v42
	ds_bpermute_b32 v39, v203, v38
	ds_bpermute_b32 v35, v203, v34
	s_waitcnt lgkmcnt(7)
	v_add_f32_e32 v68, v68, v69
	s_waitcnt lgkmcnt(6)
	v_add_f32_e32 v58, v58, v59
	s_waitcnt lgkmcnt(5)
	v_add_f32_e32 v54, v54, v55
	s_waitcnt lgkmcnt(4)
	v_add_f32_e32 v50, v50, v51
	s_waitcnt lgkmcnt(3)
	v_add_f32_e32 v46, v46, v47
	s_waitcnt lgkmcnt(2)
	v_add_f32_e32 v42, v42, v43
	s_waitcnt lgkmcnt(1)
	v_add_f32_e32 v38, v38, v39
	s_waitcnt lgkmcnt(0)
	v_add_f32_e32 v34, v34, v35
	ds_bpermute_b32 v69, v204, v68
	ds_bpermute_b32 v59, v204, v58
	ds_bpermute_b32 v55, v204, v54
	ds_bpermute_b32 v51, v204, v50
	ds_bpermute_b32 v47, v204, v46
	ds_bpermute_b32 v43, v204, v42
	ds_bpermute_b32 v39, v204, v38
	ds_bpermute_b32 v35, v204, v34
	s_waitcnt lgkmcnt(7)
	v_add_f32_e32 v68, v68, v69
	s_waitcnt lgkmcnt(6)
	v_add_f32_e32 v58, v58, v59
	s_waitcnt lgkmcnt(5)
	v_add_f32_e32 v54, v54, v55
	s_waitcnt lgkmcnt(4)
	v_add_f32_e32 v50, v50, v51
	s_waitcnt lgkmcnt(3)
	v_add_f32_e32 v46, v46, v47
	s_waitcnt lgkmcnt(2)
	v_add_f32_e32 v42, v42, v43
	s_waitcnt lgkmcnt(1)
	v_add_f32_e32 v38, v38, v39
	s_waitcnt lgkmcnt(0)
	v_add_f32_e32 v34, v34, v35
	ds_bpermute_b32 v69, v205, v68
	ds_bpermute_b32 v59, v205, v58
	ds_bpermute_b32 v55, v205, v54
	ds_bpermute_b32 v51, v205, v50
	ds_bpermute_b32 v47, v205, v46
	ds_bpermute_b32 v43, v205, v42
	ds_bpermute_b32 v39, v205, v38
	ds_bpermute_b32 v35, v205, v34
	s_waitcnt lgkmcnt(7)
	v_add_f32_e32 v68, v68, v69
	s_waitcnt lgkmcnt(6)
	v_add_f32_e32 v58, v58, v59
	s_waitcnt lgkmcnt(5)
	v_add_f32_e32 v54, v54, v55
	s_waitcnt lgkmcnt(4)
	v_add_f32_e32 v50, v50, v51
	s_waitcnt lgkmcnt(3)
	v_add_f32_e32 v46, v46, v47
	s_waitcnt lgkmcnt(2)
	v_add_f32_e32 v42, v42, v43
	s_waitcnt lgkmcnt(1)
	v_add_f32_e32 v38, v38, v39
	s_waitcnt lgkmcnt(0)
	v_add_f32_e32 v34, v34, v35
	ds_bpermute_b32 v31, v200, v30
	ds_bpermute_b32 v27, v200, v26
	ds_bpermute_b32 v23, v200, v22
	ds_bpermute_b32 v19, v200, v18
	ds_bpermute_b32 v15, v200, v14
	ds_bpermute_b32 v11, v200, v10
	ds_bpermute_b32 v7, v200, v6
	ds_bpermute_b32 v3, v200, v2
	s_waitcnt lgkmcnt(7)
	v_add_f32_e32 v30, v30, v31
	s_waitcnt lgkmcnt(6)
	v_add_f32_e32 v26, v26, v27
	s_waitcnt lgkmcnt(5)
	v_add_f32_e32 v22, v22, v23
	s_waitcnt lgkmcnt(4)
	v_add_f32_e32 v18, v18, v19
	s_waitcnt lgkmcnt(3)
	v_add_f32_e32 v14, v14, v15
	s_waitcnt lgkmcnt(2)
	v_add_f32_e32 v10, v10, v11
	s_waitcnt lgkmcnt(1)
	v_add_f32_e32 v6, v6, v7
	s_waitcnt lgkmcnt(0)
	v_add_f32_e32 v2, v2, v3
	ds_bpermute_b32 v31, v201, v30
	ds_bpermute_b32 v27, v201, v26
	ds_bpermute_b32 v23, v201, v22
	ds_bpermute_b32 v19, v201, v18
	ds_bpermute_b32 v15, v201, v14
	ds_bpermute_b32 v11, v201, v10
	ds_bpermute_b32 v7, v201, v6
	ds_bpermute_b32 v3, v201, v2
	s_waitcnt lgkmcnt(7)
	v_add_f32_e32 v30, v30, v31
	s_waitcnt lgkmcnt(6)
	v_add_f32_e32 v26, v26, v27
	s_waitcnt lgkmcnt(5)
	v_add_f32_e32 v22, v22, v23
	s_waitcnt lgkmcnt(4)
	v_add_f32_e32 v18, v18, v19
	s_waitcnt lgkmcnt(3)
	v_add_f32_e32 v14, v14, v15
	s_waitcnt lgkmcnt(2)
	v_add_f32_e32 v10, v10, v11
	s_waitcnt lgkmcnt(1)
	v_add_f32_e32 v6, v6, v7
	s_waitcnt lgkmcnt(0)
	v_add_f32_e32 v2, v2, v3
	ds_bpermute_b32 v31, v202, v30
	ds_bpermute_b32 v27, v202, v26
	ds_bpermute_b32 v23, v202, v22
	ds_bpermute_b32 v19, v202, v18
	ds_bpermute_b32 v15, v202, v14
	ds_bpermute_b32 v11, v202, v10
	ds_bpermute_b32 v7, v202, v6
	ds_bpermute_b32 v3, v202, v2
	s_waitcnt lgkmcnt(7)
	v_add_f32_e32 v30, v30, v31
	s_waitcnt lgkmcnt(6)
	v_add_f32_e32 v26, v26, v27
	s_waitcnt lgkmcnt(5)
	v_add_f32_e32 v22, v22, v23
	s_waitcnt lgkmcnt(4)
	v_add_f32_e32 v18, v18, v19
	s_waitcnt lgkmcnt(3)
	v_add_f32_e32 v14, v14, v15
	s_waitcnt lgkmcnt(2)
	v_add_f32_e32 v10, v10, v11
	s_waitcnt lgkmcnt(1)
	v_add_f32_e32 v6, v6, v7
	s_waitcnt lgkmcnt(0)
	v_add_f32_e32 v2, v2, v3
	ds_bpermute_b32 v31, v203, v30
	ds_bpermute_b32 v27, v203, v26
	ds_bpermute_b32 v23, v203, v22
	ds_bpermute_b32 v19, v203, v18
	ds_bpermute_b32 v15, v203, v14
	ds_bpermute_b32 v11, v203, v10
	ds_bpermute_b32 v7, v203, v6
	ds_bpermute_b32 v3, v203, v2
	s_waitcnt lgkmcnt(7)
	v_add_f32_e32 v30, v30, v31
	s_waitcnt lgkmcnt(6)
	v_add_f32_e32 v26, v26, v27
	s_waitcnt lgkmcnt(5)
	v_add_f32_e32 v22, v22, v23
	s_waitcnt lgkmcnt(4)
	v_add_f32_e32 v18, v18, v19
	s_waitcnt lgkmcnt(3)
	v_add_f32_e32 v14, v14, v15
	s_waitcnt lgkmcnt(2)
	v_add_f32_e32 v10, v10, v11
	s_waitcnt lgkmcnt(1)
	v_add_f32_e32 v6, v6, v7
	s_waitcnt lgkmcnt(0)
	v_add_f32_e32 v2, v2, v3
	ds_bpermute_b32 v31, v204, v30
	ds_bpermute_b32 v27, v204, v26
	ds_bpermute_b32 v23, v204, v22
	ds_bpermute_b32 v19, v204, v18
	ds_bpermute_b32 v15, v204, v14
	ds_bpermute_b32 v11, v204, v10
	ds_bpermute_b32 v7, v204, v6
	ds_bpermute_b32 v3, v204, v2
	s_waitcnt lgkmcnt(7)
	v_add_f32_e32 v30, v30, v31
	s_waitcnt lgkmcnt(6)
	v_add_f32_e32 v26, v26, v27
	s_waitcnt lgkmcnt(5)
	v_add_f32_e32 v22, v22, v23
	s_waitcnt lgkmcnt(4)
	v_add_f32_e32 v18, v18, v19
	s_waitcnt lgkmcnt(3)
	v_add_f32_e32 v14, v14, v15
	s_waitcnt lgkmcnt(2)
	v_add_f32_e32 v10, v10, v11
	s_waitcnt lgkmcnt(1)
	v_add_f32_e32 v6, v6, v7
	s_waitcnt lgkmcnt(0)
	v_add_f32_e32 v2, v2, v3
	ds_bpermute_b32 v31, v205, v30
	ds_bpermute_b32 v27, v205, v26
	ds_bpermute_b32 v23, v205, v22
	ds_bpermute_b32 v19, v205, v18
	ds_bpermute_b32 v15, v205, v14
	ds_bpermute_b32 v11, v205, v10
	ds_bpermute_b32 v7, v205, v6
	ds_bpermute_b32 v3, v205, v2
	s_waitcnt lgkmcnt(7)
	v_add_f32_e32 v30, v30, v31
	s_waitcnt lgkmcnt(6)
	v_add_f32_e32 v26, v26, v27
	s_waitcnt lgkmcnt(5)
	v_add_f32_e32 v22, v22, v23
	s_waitcnt lgkmcnt(4)
	v_add_f32_e32 v18, v18, v19
	s_waitcnt lgkmcnt(3)
	v_add_f32_e32 v14, v14, v15
	s_waitcnt lgkmcnt(2)
	v_add_f32_e32 v10, v10, v11
	s_waitcnt lgkmcnt(1)
	v_add_f32_e32 v6, v6, v7
	s_waitcnt lgkmcnt(0)
	v_add_f32_e32 v2, v2, v3
	s_add_i32 s0, s84, s60
	v_mov_b32_e32 v69, s0
	s_and_saveexec_b64 vcc, s[14:15]
	ds_write_b32 v69, v68
	s_or_b64 exec, exec, vcc
	s_and_saveexec_b64 vcc, s[16:17]
	ds_write_b32 v69, v58 offset:4
	s_or_b64 exec, exec, vcc
	s_and_saveexec_b64 vcc, s[18:19]
	ds_write_b32 v69, v54 offset:8
	s_or_b64 exec, exec, vcc
	s_and_saveexec_b64 vcc, s[20:21]
	ds_write_b32 v69, v50 offset:12
	s_or_b64 exec, exec, vcc
	s_and_saveexec_b64 vcc, s[22:23]
	ds_write_b32 v69, v46 offset:16
	s_or_b64 exec, exec, vcc
	s_and_saveexec_b64 vcc, s[24:25]
	ds_write_b32 v69, v42 offset:20
	s_or_b64 exec, exec, vcc
	s_and_saveexec_b64 vcc, s[26:27]
	ds_write_b32 v69, v38 offset:24
	s_or_b64 exec, exec, vcc
	s_and_saveexec_b64 vcc, s[28:29]
	ds_write_b32 v69, v34 offset:28
	s_or_b64 exec, exec, vcc
	s_and_saveexec_b64 vcc, s[30:31]
	ds_write_b32 v69, v30 offset:32
	s_or_b64 exec, exec, vcc
	s_and_saveexec_b64 vcc, s[34:35]
	ds_write_b32 v69, v26 offset:36
	s_or_b64 exec, exec, vcc
	s_and_saveexec_b64 vcc, s[36:37]
	ds_write_b32 v69, v22 offset:40
	s_or_b64 exec, exec, vcc
	s_and_saveexec_b64 vcc, s[38:39]
	ds_write_b32 v69, v18 offset:44
	s_or_b64 exec, exec, vcc
	s_and_saveexec_b64 vcc, s[40:41]
	ds_write_b32 v69, v14 offset:48
	s_or_b64 exec, exec, vcc
	s_and_saveexec_b64 vcc, s[42:43]
	ds_write_b32 v69, v10 offset:52
	s_or_b64 exec, exec, vcc
	s_and_saveexec_b64 vcc, s[44:45]
	ds_write_b32 v69, v6 offset:56
	s_or_b64 exec, exec, vcc
	s_and_saveexec_b64 vcc, s[46:47]
	ds_write_b32 v69, v2 offset:60
	s_branch .LBB11_2192
